# v15 plus: the second MFMA segment's 10 LDS fragment reads issued at the tail of the first softmax segment
# baseline (speedup 1.0000x reference)
; #define AT_BAR() do { __builtin_amdgcn_sched_barrier(0); asm volatile("s_waitcnt lgkmcnt(0)\n\ts_barrier" ::: "memory"); __builtin_amdgcn_sched_barrier(0); } while (0)
; #define AT_PIN_M() asm volatile("" : "+v"(p[0]), "+v"(p[1]), "+v"(o[0][0]), "+v"(o[0][1]), "+v"(o[1][0]), "+v"(o[1][1]))
; __device__ __forceinline__ void attn_phase(LAS unsigned char* lds, const bf16_t* Qb, const bf16_t* Kimg, const bf16_t* Vimg, bf16_t* AB, int bid, int G, int wave_k) {
;     ...
;         int b_prev = 2 * AT_BUF, b_cur = 0, b_next = AT_BUF;
;         AT_ISSUE(0, 0); AT_ISSUE(1, AT_BUF);
;         asm volatile("s_waitcnt vmcnt(0)" ::: "memory"); AT_BAR();
;         if (grpB) AT_BAR();
;         for (int t = 0; t < 256; ++t) {
;             AT_MSEG(b_cur, 0, (t > 0 ? b_prev : b_cur), 2);
;             AT_PIN_M();
;             AT_BAR();
;             AT_SM(t == 0);
;             AT_BAR();
;             const bool issued = (t + 2 < 256);
;             if (issued) AT_ISSUE(t + 2, b_prev);
;             AT_MSEG(b_cur, 1, b_cur, 0);
.Lph_cont_a:
	v_add_f32_e32 v234, v234, v210
	v_add_f32_e32 v237, v237, v211
	v_cvt_pk_bf16_f32 v151, v150, v151
	v_cvt_pk_bf16_f32 v150, v148, v149
	v_cvt_pk_bf16_f32 v149, v146, v147
	v_cvt_pk_bf16_f32 v148, v144, v145
	v_cvt_pk_bf16_f32 v144, v152, v153
	v_cvt_pk_bf16_f32 v145, v154, v155
	v_cvt_pk_bf16_f32 v146, v156, v157
	v_cvt_pk_bf16_f32 v147, v158, v159
	v_cvt_pk_bf16_f32 v135, v134, v135
	v_cvt_pk_bf16_f32 v134, v132, v133
	v_cvt_pk_bf16_f32 v133, v130, v131
	v_cvt_pk_bf16_f32 v132, v128, v129
	v_cvt_pk_bf16_f32 v128, v136, v137
	v_cvt_pk_bf16_f32 v129, v138, v139
	v_cvt_pk_bf16_f32 v130, v140, v141
	v_cvt_pk_bf16_f32 v131, v142, v143
	ds_read_b128 v[136:139], v160 offset:512
	ds_read_b128 v[140:143], v160 offset:2560
	ds_read_b128 v[154:157], v160 offset:4608
	ds_read_b128 v[210:213], v160 offset:6656
	ds_read_b128 v[222:225], v160 offset:8704
	ds_read_b128 v[230:233], v160 offset:10752
	ds_read_b128 v[238:241], v160 offset:12288
	ds_read_b128 v[242:245], v160 offset:12800
	ds_read_b128 v[246:249], v160 offset:14336
	ds_read_b128 v[250:253], v160 offset:14848
	s_waitcnt vmcnt(0)
	s_barrier
